# dedupe redundant 128x acc zero-init per GEMM unit (9 instances) + grid barrier: L1 invalidate issued before the spin instead of after release (all other waves parked, polls are sc1)
# speedup vs baseline: 1.0452x; 1.0142x over previous
.LBB0_323:
	s_or_b64 exec, exec, s[8:9]
	v_cvt_f32_u32_e32 v4, v2
	s_waitcnt vmcnt(0)
	v_readfirstlane_b32 s3, v3
	v_sub_u32_e32 v3, 0, v2
	v_rcp_iflag_f32_e32 v4, v4
	v_add_u32_e32 v5, s3, v1
	v_mul_f32_e32 v4, 0x4f7ffffe, v4
	v_cvt_u32_f32_e32 v4, v4
	v_mul_lo_u32 v1, v3, v4
	v_mul_hi_u32 v1, v4, v1
	v_add_u32_e32 v1, v4, v1
	v_mul_hi_u32 v1, v5, v1
	v_mul_lo_u32 v3, v1, v2
	v_sub_u32_e32 v3, v5, v3
	v_add_u32_e32 v4, 1, v1
	v_cmp_ge_u32_e32 vcc, v3, v2
	s_nop 1
	v_cndmask_b32_e32 v1, v1, v4, vcc
	v_sub_u32_e32 v4, v3, v2
	v_cndmask_b32_e32 v3, v3, v4, vcc
	v_add_u32_e32 v4, 1, v1
	v_cmp_ge_u32_e32 vcc, v3, v2
	v_add_u32_e32 v3, 1, v5
	s_nop 0
	v_cndmask_b32_e32 v1, v1, v4, vcc
	v_mul_lo_u32 v4, v2, v1
	v_add_u32_e32 v2, v4, v2
	v_cmp_ne_u32_e32 vcc, v3, v2
	s_and_saveexec_b64 s[6:7], vcc
	s_xor_b64 s[6:7], exec, s[6:7]
	s_cbranch_execz .LBB0_337
	s_waitcnt lgkmcnt(0)
	v_mov_b32_e32 v0, 0x2000
	buffer_inv sc1
	global_load_dword v0, v0, s[4:5] offset:1024 sc1
	s_add_u32 s10, s4, 0x2400
	s_addc_u32 s11, s5, 0
	s_waitcnt vmcnt(0)
	v_cmp_eq_u32_e32 vcc, v0, v1
	s_and_saveexec_b64 s[8:9], vcc
	s_cbranch_execz .LBB0_336
	s_mov_b32 s3, 1
	s_mov_b64 s[12:13], 0
	v_mov_b32_e32 v0, 0
	s_branch .LBB0_327

.LBB0_336:
	s_or_b64 exec, exec, s[8:9]
	s_waitcnt vmcnt(0)
	s_waitcnt vmcnt(0)

.LBB0_340:
	s_or_b64 exec, exec, s[8:9]
	buffer_inv sc1
	v_cvt_f32_u32_e32 v3, v0
	s_waitcnt vmcnt(1)
	v_readfirstlane_b32 s3, v2
	s_add_u32 s8, s38, 0x3500
	s_addc_u32 s9, s39, 0
	v_rcp_iflag_f32_e32 v3, v3
	v_add_u32_e32 v1, s3, v1
	v_add_u32_e32 v4, 1, v1
	s_mov_b64 s[10:11], -1
	v_mul_f32_e32 v2, 0x4f7ffffe, v3
	v_cvt_u32_f32_e32 v2, v2
	v_sub_u32_e32 v3, 0, v0
	v_mul_lo_u32 v3, v3, v2
	v_mul_hi_u32 v3, v2, v3
	v_add_u32_e32 v2, v2, v3
	v_mul_hi_u32 v2, v1, v2
	v_mul_lo_u32 v3, v2, v0
	v_sub_u32_e32 v1, v1, v3
	v_add_u32_e32 v5, 1, v2
	v_cmp_ge_u32_e32 vcc, v1, v0
	v_sub_u32_e32 v3, v1, v0
	s_nop 0
	v_cndmask_b32_e32 v2, v2, v5, vcc
	v_cndmask_b32_e32 v1, v1, v3, vcc
	v_add_u32_e32 v3, 1, v2
	v_cmp_ge_u32_e32 vcc, v1, v0
	s_nop 1
	v_cndmask_b32_e32 v2, v2, v3, vcc
	v_mul_lo_u32 v1, v0, v2
	v_add_u32_e32 v0, v1, v0
	v_cmp_ne_u32_e32 vcc, v4, v0
	v_mov_b64_e32 v[0:1], s[8:9]
	s_and_saveexec_b64 s[6:7], vcc
	s_cbranch_execz .LBB0_352
	v_mov_b32_e32 v0, 0
	global_load_dword v1, v0, s[8:9] sc1
	s_mov_b64 s[36:37], 0
	s_waitcnt vmcnt(0)
	v_cmp_eq_u32_e32 vcc, v1, v2
	s_and_saveexec_b64 s[12:13], vcc
	s_cbranch_execz .LBB0_351
	s_add_u32 s10, s38, 0x200
	s_addc_u32 s11, s39, 0
	s_mov_b32 s3, 1
	s_branch .LBB0_344

.LBB0_354:
	s_or_b64 exec, exec, s[6:7]
	s_mov_b64 s[6:7], exec
	v_mbcnt_lo_u32_b32 v0, s6, 0
	v_mbcnt_hi_u32_b32 v0, s7, v0
	v_cmp_eq_u32_e32 vcc, 0, v0
	s_waitcnt vmcnt(0)
	s_and_saveexec_b64 s[8:9], vcc
	s_cbranch_execz .LBB0_356
	s_bcnt1_i32_b64 s3, s[6:7]
	v_mov_b32_e32 v0, 0x2000
	v_mov_b32_e32 v1, s3
	global_atomic_add v0, v1, s[4:5] offset:1024

.LBB0_433:
	v_mov_b32_e32 v127, 0
	s_and_b64 vcc, exec, s[6:7]
	v_mov_b32_e32 v126, v127
	v_mov_b32_e32 v125, v127
	v_mov_b32_e32 v124, v127
	v_mov_b32_e32 v119, v127
	v_mov_b32_e32 v118, v127
	v_mov_b32_e32 v117, v127
	v_mov_b32_e32 v116, v127
	v_mov_b32_e32 v111, v127
	v_mov_b32_e32 v110, v127
	v_mov_b32_e32 v109, v127
	v_mov_b32_e32 v108, v127
	v_mov_b32_e32 v103, v127
	v_mov_b32_e32 v102, v127
	v_mov_b32_e32 v101, v127
	v_mov_b32_e32 v100, v127
	v_mov_b32_e32 v95, v127
	v_mov_b32_e32 v94, v127
	v_mov_b32_e32 v93, v127
	v_mov_b32_e32 v92, v127
	v_mov_b32_e32 v87, v127
	v_mov_b32_e32 v86, v127
	v_mov_b32_e32 v85, v127
	v_mov_b32_e32 v84, v127
	v_mov_b32_e32 v79, v127
	v_mov_b32_e32 v78, v127
	v_mov_b32_e32 v77, v127
	v_mov_b32_e32 v76, v127
	v_mov_b32_e32 v71, v127
	v_mov_b32_e32 v70, v127
	v_mov_b32_e32 v69, v127
	v_mov_b32_e32 v68, v127
	v_mov_b32_e32 v123, v127
	v_mov_b32_e32 v122, v127
	v_mov_b32_e32 v121, v127
	v_mov_b32_e32 v120, v127
	v_mov_b32_e32 v115, v127
	v_mov_b32_e32 v114, v127
	v_mov_b32_e32 v113, v127
	v_mov_b32_e32 v112, v127
	v_mov_b32_e32 v107, v127
	v_mov_b32_e32 v106, v127
	v_mov_b32_e32 v105, v127
	v_mov_b32_e32 v104, v127
	v_mov_b32_e32 v99, v127
	v_mov_b32_e32 v98, v127
	v_mov_b32_e32 v97, v127
	v_mov_b32_e32 v96, v127
	v_mov_b32_e32 v91, v127
	v_mov_b32_e32 v90, v127
	v_mov_b32_e32 v89, v127
	v_mov_b32_e32 v88, v127
	v_mov_b32_e32 v83, v127
	v_mov_b32_e32 v82, v127
	v_mov_b32_e32 v81, v127
	v_mov_b32_e32 v80, v127
	v_mov_b32_e32 v75, v127
	v_mov_b32_e32 v74, v127
	v_mov_b32_e32 v73, v127
	v_mov_b32_e32 v72, v127
	v_mov_b32_e32 v67, v127
	v_mov_b32_e32 v66, v127
	v_mov_b32_e32 v65, v127
	v_mov_b32_e32 v64, v127
	v_mov_b32_e32 v63, v127
	v_mov_b32_e32 v62, v127
	v_mov_b32_e32 v61, v127
	v_mov_b32_e32 v60, v127
	v_mov_b32_e32 v55, v127
	v_mov_b32_e32 v54, v127
	v_mov_b32_e32 v53, v127
	v_mov_b32_e32 v52, v127
	v_mov_b32_e32 v47, v127
	v_mov_b32_e32 v46, v127
	v_mov_b32_e32 v45, v127
	v_mov_b32_e32 v44, v127
	v_mov_b32_e32 v39, v127
	v_mov_b32_e32 v38, v127
	v_mov_b32_e32 v37, v127
	v_mov_b32_e32 v36, v127
	v_mov_b32_e32 v31, v127
	v_mov_b32_e32 v30, v127
	v_mov_b32_e32 v29, v127
	v_mov_b32_e32 v28, v127
	v_mov_b32_e32 v23, v127
	v_mov_b32_e32 v22, v127
	v_mov_b32_e32 v21, v127
	v_mov_b32_e32 v20, v127
	v_mov_b32_e32 v15, v127
	v_mov_b32_e32 v14, v127
	v_mov_b32_e32 v13, v127
	v_mov_b32_e32 v12, v127
	v_mov_b32_e32 v7, v127
	v_mov_b32_e32 v6, v127
	v_mov_b32_e32 v5, v127
	v_mov_b32_e32 v4, v127
	v_mov_b32_e32 v59, v127
	v_mov_b32_e32 v58, v127
	v_mov_b32_e32 v57, v127
	v_mov_b32_e32 v56, v127
	v_mov_b32_e32 v51, v127
	v_mov_b32_e32 v50, v127
	v_mov_b32_e32 v49, v127
	v_mov_b32_e32 v48, v127
	v_mov_b32_e32 v43, v127
	v_mov_b32_e32 v42, v127
	v_mov_b32_e32 v41, v127
	v_mov_b32_e32 v40, v127
	v_mov_b32_e32 v35, v127
	v_mov_b32_e32 v34, v127
	v_mov_b32_e32 v33, v127
	v_mov_b32_e32 v32, v127
	v_mov_b32_e32 v27, v127
	v_mov_b32_e32 v26, v127
	v_mov_b32_e32 v25, v127
	v_mov_b32_e32 v24, v127
	v_mov_b32_e32 v19, v127
	v_mov_b32_e32 v18, v127
	v_mov_b32_e32 v17, v127
	v_mov_b32_e32 v16, v127
	v_mov_b32_e32 v11, v127
	v_mov_b32_e32 v10, v127
	v_mov_b32_e32 v9, v127
	v_mov_b32_e32 v8, v127
	v_mov_b32_e32 v3, v127
	v_mov_b32_e32 v2, v127
	v_mov_b32_e32 v1, v127
	v_mov_b32_e32 v0, v127
	s_cbranch_vccnz .LBB0_436
	s_add_u32 s92, s92, 0x80
	s_addc_u32 s93, s93, 0
	s_add_u32 s91, s94, 0x100
	s_addc_u32 vcc_lo, s95, 0
	s_mov_b32 s94, 0

.LBB0_796:
	s_or_b64 exec, exec, s[8:9]
	buffer_inv sc1
	v_cvt_f32_u32_e32 v3, v0
	s_waitcnt vmcnt(1)
	v_readfirstlane_b32 s3, v2
	s_add_u32 s8, s38, 0x3500
	s_addc_u32 s9, s39, 0
	v_rcp_iflag_f32_e32 v3, v3
	v_add_u32_e32 v1, s3, v1
	v_add_u32_e32 v4, 1, v1
	s_mov_b64 s[10:11], -1
	v_mul_f32_e32 v2, 0x4f7ffffe, v3
	v_cvt_u32_f32_e32 v2, v2
	v_sub_u32_e32 v3, 0, v0
	v_mul_lo_u32 v3, v3, v2
	v_mul_hi_u32 v3, v2, v3
	v_add_u32_e32 v2, v2, v3
	v_mul_hi_u32 v2, v1, v2
	v_mul_lo_u32 v3, v2, v0
	v_sub_u32_e32 v1, v1, v3
	v_add_u32_e32 v5, 1, v2
	v_cmp_ge_u32_e32 vcc, v1, v0
	v_sub_u32_e32 v3, v1, v0
	s_nop 0
	v_cndmask_b32_e32 v2, v2, v5, vcc
	v_cndmask_b32_e32 v1, v1, v3, vcc
	v_add_u32_e32 v3, 1, v2
	v_cmp_ge_u32_e32 vcc, v1, v0
	s_nop 1
	v_cndmask_b32_e32 v2, v2, v3, vcc
	v_mul_lo_u32 v1, v0, v2
	v_add_u32_e32 v0, v1, v0
	v_cmp_ne_u32_e32 vcc, v4, v0
	v_mov_b64_e32 v[0:1], s[8:9]
	s_and_saveexec_b64 s[6:7], vcc
	s_cbranch_execz .LBB0_808
	v_mov_b32_e32 v0, 0
	global_load_dword v1, v0, s[8:9] sc1
	s_mov_b64 s[14:15], 0
	s_waitcnt vmcnt(0)
	v_cmp_eq_u32_e32 vcc, v1, v2
	s_and_saveexec_b64 s[12:13], vcc
	s_cbranch_execz .LBB0_807
	s_add_u32 s10, s38, 0x200
	s_addc_u32 s11, s39, 0
	s_mov_b32 s3, 1
	s_branch .LBB0_800

.LBB0_835:
	v_mov_b32_e32 v127, 0
	s_and_b64 vcc, exec, s[4:5]
	v_mov_b32_e32 v126, v127
	v_mov_b32_e32 v125, v127
	v_mov_b32_e32 v124, v127
	v_mov_b32_e32 v123, v127
	v_mov_b32_e32 v122, v127
	v_mov_b32_e32 v121, v127
	v_mov_b32_e32 v120, v127
	v_mov_b32_e32 v111, v127
	v_mov_b32_e32 v110, v127
	v_mov_b32_e32 v109, v127
	v_mov_b32_e32 v108, v127
	v_mov_b32_e32 v107, v127
	v_mov_b32_e32 v106, v127
	v_mov_b32_e32 v105, v127
	v_mov_b32_e32 v104, v127
	v_mov_b32_e32 v95, v127
	v_mov_b32_e32 v94, v127
	v_mov_b32_e32 v93, v127
	v_mov_b32_e32 v92, v127
	v_mov_b32_e32 v91, v127
	v_mov_b32_e32 v90, v127
	v_mov_b32_e32 v89, v127
	v_mov_b32_e32 v88, v127
	v_mov_b32_e32 v79, v127
	v_mov_b32_e32 v78, v127
	v_mov_b32_e32 v77, v127
	v_mov_b32_e32 v76, v127
	v_mov_b32_e32 v75, v127
	v_mov_b32_e32 v74, v127
	v_mov_b32_e32 v73, v127
	v_mov_b32_e32 v72, v127
	v_mov_b32_e32 v119, v127
	v_mov_b32_e32 v118, v127
	v_mov_b32_e32 v117, v127
	v_mov_b32_e32 v116, v127
	v_mov_b32_e32 v115, v127
	v_mov_b32_e32 v114, v127
	v_mov_b32_e32 v113, v127
	v_mov_b32_e32 v112, v127
	v_mov_b32_e32 v103, v127
	v_mov_b32_e32 v102, v127
	v_mov_b32_e32 v101, v127
	v_mov_b32_e32 v100, v127
	v_mov_b32_e32 v99, v127
	v_mov_b32_e32 v98, v127
	v_mov_b32_e32 v97, v127
	v_mov_b32_e32 v96, v127
	v_mov_b32_e32 v87, v127
	v_mov_b32_e32 v86, v127
	v_mov_b32_e32 v85, v127
	v_mov_b32_e32 v84, v127
	v_mov_b32_e32 v83, v127
	v_mov_b32_e32 v82, v127
	v_mov_b32_e32 v81, v127
	v_mov_b32_e32 v80, v127
	v_mov_b32_e32 v71, v127
	v_mov_b32_e32 v70, v127
	v_mov_b32_e32 v69, v127
	v_mov_b32_e32 v68, v127
	v_mov_b32_e32 v67, v127
	v_mov_b32_e32 v66, v127
	v_mov_b32_e32 v65, v127
	v_mov_b32_e32 v64, v127
	v_mov_b32_e32 v63, v127
	v_mov_b32_e32 v62, v127
	v_mov_b32_e32 v61, v127
	v_mov_b32_e32 v60, v127
	v_mov_b32_e32 v59, v127
	v_mov_b32_e32 v58, v127
	v_mov_b32_e32 v57, v127
	v_mov_b32_e32 v56, v127
	v_mov_b32_e32 v47, v127
	v_mov_b32_e32 v46, v127
	v_mov_b32_e32 v45, v127
	v_mov_b32_e32 v44, v127
	v_mov_b32_e32 v43, v127
	v_mov_b32_e32 v42, v127
	v_mov_b32_e32 v41, v127
	v_mov_b32_e32 v40, v127
	v_mov_b32_e32 v31, v127
	v_mov_b32_e32 v30, v127
	v_mov_b32_e32 v29, v127
	v_mov_b32_e32 v28, v127
	v_mov_b32_e32 v27, v127
	v_mov_b32_e32 v26, v127
	v_mov_b32_e32 v25, v127
	v_mov_b32_e32 v24, v127
	v_mov_b32_e32 v15, v127
	v_mov_b32_e32 v14, v127
	v_mov_b32_e32 v13, v127
	v_mov_b32_e32 v12, v127
	v_mov_b32_e32 v11, v127
	v_mov_b32_e32 v10, v127
	v_mov_b32_e32 v9, v127
	v_mov_b32_e32 v8, v127
	v_mov_b32_e32 v55, v127
	v_mov_b32_e32 v54, v127
	v_mov_b32_e32 v53, v127
	v_mov_b32_e32 v52, v127
	v_mov_b32_e32 v51, v127
	v_mov_b32_e32 v50, v127
	v_mov_b32_e32 v49, v127
	v_mov_b32_e32 v48, v127
	v_mov_b32_e32 v39, v127
	v_mov_b32_e32 v38, v127
	v_mov_b32_e32 v37, v127
	v_mov_b32_e32 v36, v127
	v_mov_b32_e32 v35, v127
	v_mov_b32_e32 v34, v127
	v_mov_b32_e32 v33, v127
	v_mov_b32_e32 v32, v127
	v_mov_b32_e32 v23, v127
	v_mov_b32_e32 v22, v127
	v_mov_b32_e32 v21, v127
	v_mov_b32_e32 v20, v127
	v_mov_b32_e32 v19, v127
	v_mov_b32_e32 v18, v127
	v_mov_b32_e32 v17, v127
	v_mov_b32_e32 v16, v127
	v_mov_b32_e32 v7, v127
	v_mov_b32_e32 v6, v127
	s_waitcnt lgkmcnt(0)
	v_mov_b32_e32 v5, v127
	v_mov_b32_e32 v4, v127
	v_mov_b32_e32 v3, v127
	v_mov_b32_e32 v2, v127
	v_mov_b32_e32 v1, v127
	v_mov_b32_e32 v0, v127
	s_cbranch_vccnz .LBB0_838
	s_add_u32 s74, s74, 0x80
	s_addc_u32 s75, s75, 0
	s_add_u32 s3, s76, 0x100
	s_addc_u32 s9, s77, 0
	s_mov_b32 s76, 0

.LBB0_1219:
	v_mov_b32_e32 v127, 0
	s_and_b64 vcc, exec, s[4:5]
	v_mov_b32_e32 v126, v127
	v_mov_b32_e32 v125, v127
	v_mov_b32_e32 v124, v127
	v_mov_b32_e32 v123, v127
	v_mov_b32_e32 v122, v127
	v_mov_b32_e32 v121, v127
	v_mov_b32_e32 v120, v127
	v_mov_b32_e32 v111, v127
	v_mov_b32_e32 v110, v127
	v_mov_b32_e32 v109, v127
	v_mov_b32_e32 v108, v127
	v_mov_b32_e32 v107, v127
	v_mov_b32_e32 v106, v127
	v_mov_b32_e32 v105, v127
	v_mov_b32_e32 v104, v127
	v_mov_b32_e32 v95, v127
	v_mov_b32_e32 v94, v127
	v_mov_b32_e32 v93, v127
	v_mov_b32_e32 v92, v127
	v_mov_b32_e32 v91, v127
	v_mov_b32_e32 v90, v127
	v_mov_b32_e32 v89, v127
	v_mov_b32_e32 v88, v127
	v_mov_b32_e32 v79, v127
	v_mov_b32_e32 v78, v127
	v_mov_b32_e32 v77, v127
	v_mov_b32_e32 v76, v127
	v_mov_b32_e32 v75, v127
	v_mov_b32_e32 v74, v127
	v_mov_b32_e32 v73, v127
	v_mov_b32_e32 v72, v127
	v_mov_b32_e32 v119, v127
	v_mov_b32_e32 v118, v127
	v_mov_b32_e32 v117, v127
	v_mov_b32_e32 v116, v127
	v_mov_b32_e32 v115, v127
	v_mov_b32_e32 v114, v127
	v_mov_b32_e32 v113, v127
	v_mov_b32_e32 v112, v127
	v_mov_b32_e32 v103, v127
	v_mov_b32_e32 v102, v127
	v_mov_b32_e32 v101, v127
	v_mov_b32_e32 v100, v127
	v_mov_b32_e32 v99, v127
	v_mov_b32_e32 v98, v127
	v_mov_b32_e32 v97, v127
	v_mov_b32_e32 v96, v127
	v_mov_b32_e32 v87, v127
	v_mov_b32_e32 v86, v127
	v_mov_b32_e32 v85, v127
	v_mov_b32_e32 v84, v127
	v_mov_b32_e32 v83, v127
	v_mov_b32_e32 v82, v127
	v_mov_b32_e32 v81, v127
	v_mov_b32_e32 v80, v127
	v_mov_b32_e32 v71, v127
	v_mov_b32_e32 v70, v127
	v_mov_b32_e32 v69, v127
	v_mov_b32_e32 v68, v127
	v_mov_b32_e32 v67, v127
	v_mov_b32_e32 v66, v127
	v_mov_b32_e32 v65, v127
	v_mov_b32_e32 v64, v127
	v_mov_b32_e32 v63, v127
	v_mov_b32_e32 v62, v127
	v_mov_b32_e32 v61, v127
	v_mov_b32_e32 v60, v127
	v_mov_b32_e32 v59, v127
	v_mov_b32_e32 v58, v127
	v_mov_b32_e32 v57, v127
	v_mov_b32_e32 v56, v127
	v_mov_b32_e32 v47, v127
	v_mov_b32_e32 v46, v127
	v_mov_b32_e32 v45, v127
	v_mov_b32_e32 v44, v127
	v_mov_b32_e32 v43, v127
	v_mov_b32_e32 v42, v127
	v_mov_b32_e32 v41, v127
	v_mov_b32_e32 v40, v127
	v_mov_b32_e32 v31, v127
	v_mov_b32_e32 v30, v127
	v_mov_b32_e32 v29, v127
	v_mov_b32_e32 v28, v127
	v_mov_b32_e32 v27, v127
	v_mov_b32_e32 v26, v127
	v_mov_b32_e32 v25, v127
	v_mov_b32_e32 v24, v127
	v_mov_b32_e32 v15, v127
	v_mov_b32_e32 v14, v127
	v_mov_b32_e32 v13, v127
	v_mov_b32_e32 v12, v127
	v_mov_b32_e32 v11, v127
	v_mov_b32_e32 v10, v127
	v_mov_b32_e32 v9, v127
	v_mov_b32_e32 v8, v127
	v_mov_b32_e32 v55, v127
	v_mov_b32_e32 v54, v127
	v_mov_b32_e32 v53, v127
	v_mov_b32_e32 v52, v127
	v_mov_b32_e32 v51, v127
	v_mov_b32_e32 v50, v127
	v_mov_b32_e32 v49, v127
	v_mov_b32_e32 v48, v127
	v_mov_b32_e32 v39, v127
	v_mov_b32_e32 v38, v127
	v_mov_b32_e32 v37, v127
	v_mov_b32_e32 v36, v127
	v_mov_b32_e32 v35, v127
	v_mov_b32_e32 v34, v127
	v_mov_b32_e32 v33, v127
	v_mov_b32_e32 v32, v127
	v_mov_b32_e32 v23, v127
	v_mov_b32_e32 v22, v127
	v_mov_b32_e32 v21, v127
	v_mov_b32_e32 v20, v127
	v_mov_b32_e32 v19, v127
	v_mov_b32_e32 v18, v127
	v_mov_b32_e32 v17, v127
	v_mov_b32_e32 v16, v127
	v_mov_b32_e32 v7, v127
	v_mov_b32_e32 v6, v127
	v_mov_b32_e32 v5, v127
	v_mov_b32_e32 v4, v127
	v_mov_b32_e32 v3, v127
	v_mov_b32_e32 v2, v127
	v_mov_b32_e32 v1, v127
	v_mov_b32_e32 v0, v127
	s_cbranch_vccnz .LBB0_1222
	s_add_u32 s0, s10, 0x80
	s_addc_u32 s1, s11, 0
	s_add_u32 s10, s8, 0x100
	s_addc_u32 s11, s9, 0
	s_mov_b32 s8, 0

.LBB0_1287:
	v_mov_b32_e32 v127, 0
	s_and_b64 vcc, exec, s[6:7]
	v_mov_b32_e32 v126, v127
	v_mov_b32_e32 v125, v127
	v_mov_b32_e32 v124, v127
	v_mov_b32_e32 v123, v127
	v_mov_b32_e32 v122, v127
	v_mov_b32_e32 v121, v127
	v_mov_b32_e32 v120, v127
	v_mov_b32_e32 v111, v127
	v_mov_b32_e32 v110, v127
	v_mov_b32_e32 v109, v127
	v_mov_b32_e32 v108, v127
	v_mov_b32_e32 v107, v127
	v_mov_b32_e32 v106, v127
	v_mov_b32_e32 v105, v127
	v_mov_b32_e32 v104, v127
	v_mov_b32_e32 v95, v127
	v_mov_b32_e32 v94, v127
	v_mov_b32_e32 v93, v127
	v_mov_b32_e32 v92, v127
	v_mov_b32_e32 v91, v127
	v_mov_b32_e32 v90, v127
	v_mov_b32_e32 v89, v127
	v_mov_b32_e32 v88, v127
	v_mov_b32_e32 v79, v127
	v_mov_b32_e32 v78, v127
	v_mov_b32_e32 v77, v127
	v_mov_b32_e32 v76, v127
	v_mov_b32_e32 v75, v127
	v_mov_b32_e32 v74, v127
	v_mov_b32_e32 v73, v127
	v_mov_b32_e32 v72, v127
	v_mov_b32_e32 v119, v127
	v_mov_b32_e32 v118, v127
	v_mov_b32_e32 v117, v127
	v_mov_b32_e32 v116, v127
	v_mov_b32_e32 v115, v127
	v_mov_b32_e32 v114, v127
	v_mov_b32_e32 v113, v127
	v_mov_b32_e32 v112, v127
	v_mov_b32_e32 v103, v127
	v_mov_b32_e32 v102, v127
	v_mov_b32_e32 v101, v127
	v_mov_b32_e32 v100, v127
	v_mov_b32_e32 v99, v127
	v_mov_b32_e32 v98, v127
	v_mov_b32_e32 v97, v127
	v_mov_b32_e32 v96, v127
	v_mov_b32_e32 v87, v127
	v_mov_b32_e32 v86, v127
	v_mov_b32_e32 v85, v127
	v_mov_b32_e32 v84, v127
	v_mov_b32_e32 v83, v127
	v_mov_b32_e32 v82, v127
	v_mov_b32_e32 v81, v127
	v_mov_b32_e32 v80, v127
	v_mov_b32_e32 v71, v127
	v_mov_b32_e32 v70, v127
	v_mov_b32_e32 v69, v127
	v_mov_b32_e32 v68, v127
	v_mov_b32_e32 v67, v127
	v_mov_b32_e32 v66, v127
	v_mov_b32_e32 v65, v127
	v_mov_b32_e32 v64, v127
	v_mov_b32_e32 v63, v127
	v_mov_b32_e32 v62, v127
	v_mov_b32_e32 v61, v127
	v_mov_b32_e32 v60, v127
	v_mov_b32_e32 v59, v127
	v_mov_b32_e32 v58, v127
	v_mov_b32_e32 v57, v127
	v_mov_b32_e32 v56, v127
	v_mov_b32_e32 v47, v127
	v_mov_b32_e32 v46, v127
	v_mov_b32_e32 v45, v127
	v_mov_b32_e32 v44, v127
	v_mov_b32_e32 v43, v127
	v_mov_b32_e32 v42, v127
	v_mov_b32_e32 v41, v127
	v_mov_b32_e32 v40, v127
	v_mov_b32_e32 v31, v127
	v_mov_b32_e32 v30, v127
	v_mov_b32_e32 v29, v127
	v_mov_b32_e32 v28, v127
	v_mov_b32_e32 v27, v127
	v_mov_b32_e32 v26, v127
	v_mov_b32_e32 v25, v127
	v_mov_b32_e32 v24, v127
	v_mov_b32_e32 v15, v127
	v_mov_b32_e32 v14, v127
	v_mov_b32_e32 v13, v127
	v_mov_b32_e32 v12, v127
	v_mov_b32_e32 v11, v127
	v_mov_b32_e32 v10, v127
	v_mov_b32_e32 v9, v127
	v_mov_b32_e32 v8, v127
	v_mov_b32_e32 v55, v127
	v_mov_b32_e32 v54, v127
	v_mov_b32_e32 v53, v127
	v_mov_b32_e32 v52, v127
	v_mov_b32_e32 v51, v127
	v_mov_b32_e32 v50, v127
	v_mov_b32_e32 v49, v127
	v_mov_b32_e32 v48, v127
	v_mov_b32_e32 v39, v127
	v_mov_b32_e32 v38, v127
	v_mov_b32_e32 v37, v127
	v_mov_b32_e32 v36, v127
	v_mov_b32_e32 v35, v127
	v_mov_b32_e32 v34, v127
	v_mov_b32_e32 v33, v127
	v_mov_b32_e32 v32, v127
	v_mov_b32_e32 v23, v127
	v_mov_b32_e32 v22, v127
	v_mov_b32_e32 v21, v127
	v_mov_b32_e32 v20, v127
	v_mov_b32_e32 v19, v127
	v_mov_b32_e32 v18, v127
	v_mov_b32_e32 v17, v127
	v_mov_b32_e32 v16, v127
	v_mov_b32_e32 v7, v127
	v_mov_b32_e32 v6, v127
	v_mov_b32_e32 v5, v127
	v_mov_b32_e32 v4, v127
	v_mov_b32_e32 v3, v127
	v_mov_b32_e32 v2, v127
	v_mov_b32_e32 v1, v127
	v_mov_b32_e32 v0, v127
	s_cbranch_vccnz .LBB0_1290
	s_add_u32 s52, s90, 0x80
	s_addc_u32 s53, s91, 0
	s_add_u32 s90, s78, 0x100
	s_addc_u32 s91, s79, 0
	s_mov_b32 s66, 0

.LBB0_1482:
	v_mov_b32_e32 v127, 0
	s_and_b64 vcc, exec, s[4:5]
	v_mov_b32_e32 v126, v127
	v_mov_b32_e32 v125, v127
	v_mov_b32_e32 v124, v127
	v_mov_b32_e32 v123, v127
	v_mov_b32_e32 v122, v127
	v_mov_b32_e32 v121, v127
	v_mov_b32_e32 v120, v127
	v_mov_b32_e32 v111, v127
	v_mov_b32_e32 v110, v127
	v_mov_b32_e32 v109, v127
	v_mov_b32_e32 v108, v127
	v_mov_b32_e32 v107, v127
	v_mov_b32_e32 v106, v127
	v_mov_b32_e32 v105, v127
	v_mov_b32_e32 v104, v127
	v_mov_b32_e32 v95, v127
	v_mov_b32_e32 v94, v127
	v_mov_b32_e32 v93, v127
	v_mov_b32_e32 v92, v127
	v_mov_b32_e32 v91, v127
	v_mov_b32_e32 v90, v127
	v_mov_b32_e32 v89, v127
	v_mov_b32_e32 v88, v127
	v_mov_b32_e32 v79, v127
	v_mov_b32_e32 v78, v127
	v_mov_b32_e32 v77, v127
	v_mov_b32_e32 v76, v127
	v_mov_b32_e32 v75, v127
	v_mov_b32_e32 v74, v127
	v_mov_b32_e32 v73, v127
	v_mov_b32_e32 v72, v127
	v_mov_b32_e32 v119, v127
	v_mov_b32_e32 v118, v127
	v_mov_b32_e32 v117, v127
	v_mov_b32_e32 v116, v127
	v_mov_b32_e32 v115, v127
	v_mov_b32_e32 v114, v127
	v_mov_b32_e32 v113, v127
	v_mov_b32_e32 v112, v127
	v_mov_b32_e32 v103, v127
	v_mov_b32_e32 v102, v127
	v_mov_b32_e32 v101, v127
	v_mov_b32_e32 v100, v127
	v_mov_b32_e32 v99, v127
	v_mov_b32_e32 v98, v127
	v_mov_b32_e32 v97, v127
	v_mov_b32_e32 v96, v127
	v_mov_b32_e32 v87, v127
	v_mov_b32_e32 v86, v127
	v_mov_b32_e32 v85, v127
	v_mov_b32_e32 v84, v127
	v_mov_b32_e32 v83, v127
	v_mov_b32_e32 v82, v127
	v_mov_b32_e32 v81, v127
	v_mov_b32_e32 v80, v127
	v_mov_b32_e32 v71, v127
	v_mov_b32_e32 v70, v127
	v_mov_b32_e32 v69, v127
	v_mov_b32_e32 v68, v127
	v_mov_b32_e32 v67, v127
	v_mov_b32_e32 v66, v127
	v_mov_b32_e32 v65, v127
	v_mov_b32_e32 v64, v127
	v_mov_b32_e32 v63, v127
	v_mov_b32_e32 v62, v127
	v_mov_b32_e32 v61, v127
	v_mov_b32_e32 v60, v127
	v_mov_b32_e32 v59, v127
	v_mov_b32_e32 v58, v127
	v_mov_b32_e32 v57, v127
	v_mov_b32_e32 v56, v127
	v_mov_b32_e32 v47, v127
	v_mov_b32_e32 v46, v127
	v_mov_b32_e32 v45, v127
	v_mov_b32_e32 v44, v127
	v_mov_b32_e32 v43, v127
	v_mov_b32_e32 v42, v127
	v_mov_b32_e32 v41, v127
	v_mov_b32_e32 v40, v127
	v_mov_b32_e32 v31, v127
	v_mov_b32_e32 v30, v127
	v_mov_b32_e32 v29, v127
	v_mov_b32_e32 v28, v127
	v_mov_b32_e32 v27, v127
	v_mov_b32_e32 v26, v127
	v_mov_b32_e32 v25, v127
	v_mov_b32_e32 v24, v127
	v_mov_b32_e32 v15, v127
	v_mov_b32_e32 v14, v127
	v_mov_b32_e32 v13, v127
	v_mov_b32_e32 v12, v127
	v_mov_b32_e32 v11, v127
	v_mov_b32_e32 v10, v127
	v_mov_b32_e32 v9, v127
	v_mov_b32_e32 v8, v127
	v_mov_b32_e32 v55, v127
	v_mov_b32_e32 v54, v127
	v_mov_b32_e32 v53, v127
	v_mov_b32_e32 v52, v127
	v_mov_b32_e32 v51, v127
	v_mov_b32_e32 v50, v127
	v_mov_b32_e32 v49, v127
	v_mov_b32_e32 v48, v127
	v_mov_b32_e32 v39, v127
	v_mov_b32_e32 v38, v127
	v_mov_b32_e32 v37, v127
	v_mov_b32_e32 v36, v127
	v_mov_b32_e32 v35, v127
	v_mov_b32_e32 v34, v127
	v_mov_b32_e32 v33, v127
	v_mov_b32_e32 v32, v127
	v_mov_b32_e32 v23, v127
	v_mov_b32_e32 v22, v127
	v_mov_b32_e32 v21, v127
	v_mov_b32_e32 v20, v127
	v_mov_b32_e32 v19, v127
	v_mov_b32_e32 v18, v127
	v_mov_b32_e32 v17, v127
	v_mov_b32_e32 v16, v127
	v_mov_b32_e32 v7, v127
	v_mov_b32_e32 v6, v127
	v_mov_b32_e32 v5, v127
	v_mov_b32_e32 v4, v127
	v_mov_b32_e32 v3, v127
	v_mov_b32_e32 v2, v127
	v_mov_b32_e32 v1, v127
	v_mov_b32_e32 v0, v127
	s_cbranch_vccnz .LBB0_1485
	s_add_u32 s48, s48, 0x80
	s_addc_u32 s49, s49, 0
	s_add_u32 s47, s50, 0x100
	s_addc_u32 s83, s51, 0
	s_mov_b32 s50, 0

.LBB0_1511:
	v_mov_b32_e32 v127, 0
	s_and_b64 vcc, exec, s[4:5]
	v_mov_b32_e32 v126, v127
	v_mov_b32_e32 v125, v127
	v_mov_b32_e32 v124, v127
	v_mov_b32_e32 v123, v127
	v_mov_b32_e32 v122, v127
	v_mov_b32_e32 v121, v127
	v_mov_b32_e32 v120, v127
	v_mov_b32_e32 v111, v127
	v_mov_b32_e32 v110, v127
	v_mov_b32_e32 v109, v127
	v_mov_b32_e32 v108, v127
	v_mov_b32_e32 v107, v127
	v_mov_b32_e32 v106, v127
	v_mov_b32_e32 v105, v127
	v_mov_b32_e32 v104, v127
	v_mov_b32_e32 v95, v127
	v_mov_b32_e32 v94, v127
	v_mov_b32_e32 v93, v127
	v_mov_b32_e32 v92, v127
	v_mov_b32_e32 v91, v127
	v_mov_b32_e32 v90, v127
	v_mov_b32_e32 v89, v127
	v_mov_b32_e32 v88, v127
	v_mov_b32_e32 v79, v127
	v_mov_b32_e32 v78, v127
	v_mov_b32_e32 v77, v127
	v_mov_b32_e32 v76, v127
	v_mov_b32_e32 v75, v127
	v_mov_b32_e32 v74, v127
	v_mov_b32_e32 v73, v127
	v_mov_b32_e32 v72, v127
	v_mov_b32_e32 v119, v127
	v_mov_b32_e32 v118, v127
	v_mov_b32_e32 v117, v127
	v_mov_b32_e32 v116, v127
	v_mov_b32_e32 v115, v127
	v_mov_b32_e32 v114, v127
	v_mov_b32_e32 v113, v127
	v_mov_b32_e32 v112, v127
	v_mov_b32_e32 v103, v127
	v_mov_b32_e32 v102, v127
	v_mov_b32_e32 v101, v127
	v_mov_b32_e32 v100, v127
	v_mov_b32_e32 v99, v127
	v_mov_b32_e32 v98, v127
	v_mov_b32_e32 v97, v127
	v_mov_b32_e32 v96, v127
	v_mov_b32_e32 v87, v127
	v_mov_b32_e32 v86, v127
	v_mov_b32_e32 v85, v127
	v_mov_b32_e32 v84, v127
	v_mov_b32_e32 v83, v127
	v_mov_b32_e32 v82, v127
	v_mov_b32_e32 v81, v127
	v_mov_b32_e32 v80, v127
	v_mov_b32_e32 v71, v127
	v_mov_b32_e32 v70, v127
	v_mov_b32_e32 v69, v127
	v_mov_b32_e32 v68, v127
	v_mov_b32_e32 v67, v127
	v_mov_b32_e32 v66, v127
	v_mov_b32_e32 v65, v127
	v_mov_b32_e32 v64, v127
	v_mov_b32_e32 v63, v127
	v_mov_b32_e32 v62, v127
	v_mov_b32_e32 v61, v127
	v_mov_b32_e32 v60, v127
	v_mov_b32_e32 v59, v127
	v_mov_b32_e32 v58, v127
	v_mov_b32_e32 v57, v127
	v_mov_b32_e32 v56, v127
	v_mov_b32_e32 v47, v127
	v_mov_b32_e32 v46, v127
	v_mov_b32_e32 v45, v127
	v_mov_b32_e32 v44, v127
	v_mov_b32_e32 v43, v127
	v_mov_b32_e32 v42, v127
	v_mov_b32_e32 v41, v127
	v_mov_b32_e32 v40, v127
	v_mov_b32_e32 v31, v127
	v_mov_b32_e32 v30, v127
	v_mov_b32_e32 v29, v127
	v_mov_b32_e32 v28, v127
	v_mov_b32_e32 v27, v127
	v_mov_b32_e32 v26, v127
	v_mov_b32_e32 v25, v127
	v_mov_b32_e32 v24, v127
	v_mov_b32_e32 v15, v127
	v_mov_b32_e32 v14, v127
	v_mov_b32_e32 v13, v127
	v_mov_b32_e32 v12, v127
	v_mov_b32_e32 v11, v127
	v_mov_b32_e32 v10, v127
	v_mov_b32_e32 v9, v127
	v_mov_b32_e32 v8, v127
	v_mov_b32_e32 v55, v127
	v_mov_b32_e32 v54, v127
	v_mov_b32_e32 v53, v127
	v_mov_b32_e32 v52, v127
	v_mov_b32_e32 v51, v127
	v_mov_b32_e32 v50, v127
	v_mov_b32_e32 v49, v127
	v_mov_b32_e32 v48, v127
	v_mov_b32_e32 v39, v127
	v_mov_b32_e32 v38, v127
	v_mov_b32_e32 v37, v127
	v_mov_b32_e32 v36, v127
	v_mov_b32_e32 v35, v127
	v_mov_b32_e32 v34, v127
	v_mov_b32_e32 v33, v127
	v_mov_b32_e32 v32, v127
	v_mov_b32_e32 v23, v127
	v_mov_b32_e32 v22, v127
	v_mov_b32_e32 v21, v127
	v_mov_b32_e32 v20, v127
	v_mov_b32_e32 v19, v127
	v_mov_b32_e32 v18, v127
	v_mov_b32_e32 v17, v127
	v_mov_b32_e32 v16, v127
	v_mov_b32_e32 v7, v127
	v_mov_b32_e32 v6, v127
	v_mov_b32_e32 v5, v127
	v_mov_b32_e32 v4, v127
	v_mov_b32_e32 v3, v127
	v_mov_b32_e32 v2, v127
	v_mov_b32_e32 v1, v127
	v_mov_b32_e32 v0, v127
	s_cbranch_vccnz .LBB0_1514
	s_add_u32 s48, s48, 0x80
	s_addc_u32 s49, s49, 0
	s_add_u32 s47, s50, 0x100
	s_addc_u32 s80, s51, 0
	s_mov_b32 s50, 0

.LBB0_1594:
	v_mov_b32_e32 v127, 0
	s_and_b64 vcc, exec, s[4:5]
	v_mov_b32_e32 v126, v127
	v_mov_b32_e32 v125, v127
	v_mov_b32_e32 v124, v127
	v_mov_b32_e32 v123, v127
	v_mov_b32_e32 v122, v127
	v_mov_b32_e32 v121, v127
	v_mov_b32_e32 v120, v127
	v_mov_b32_e32 v111, v127
	v_mov_b32_e32 v110, v127
	v_mov_b32_e32 v109, v127
	v_mov_b32_e32 v108, v127
	v_mov_b32_e32 v107, v127
	v_mov_b32_e32 v106, v127
	v_mov_b32_e32 v105, v127
	v_mov_b32_e32 v104, v127
	v_mov_b32_e32 v95, v127
	v_mov_b32_e32 v94, v127
	v_mov_b32_e32 v93, v127
	v_mov_b32_e32 v92, v127
	v_mov_b32_e32 v91, v127
	v_mov_b32_e32 v90, v127
	v_mov_b32_e32 v89, v127
	v_mov_b32_e32 v88, v127
	v_mov_b32_e32 v79, v127
	v_mov_b32_e32 v78, v127
	v_mov_b32_e32 v77, v127
	v_mov_b32_e32 v76, v127
	v_mov_b32_e32 v75, v127
	v_mov_b32_e32 v74, v127
	v_mov_b32_e32 v73, v127
	v_mov_b32_e32 v72, v127
	v_mov_b32_e32 v119, v127
	v_mov_b32_e32 v118, v127
	v_mov_b32_e32 v117, v127
	v_mov_b32_e32 v116, v127
	v_mov_b32_e32 v115, v127
	v_mov_b32_e32 v114, v127
	v_mov_b32_e32 v113, v127
	v_mov_b32_e32 v112, v127
	v_mov_b32_e32 v103, v127
	v_mov_b32_e32 v102, v127
	v_mov_b32_e32 v101, v127
	v_mov_b32_e32 v100, v127
	v_mov_b32_e32 v99, v127
	v_mov_b32_e32 v98, v127
	v_mov_b32_e32 v97, v127
	v_mov_b32_e32 v96, v127
	v_mov_b32_e32 v87, v127
	v_mov_b32_e32 v86, v127
	v_mov_b32_e32 v85, v127
	v_mov_b32_e32 v84, v127
	v_mov_b32_e32 v83, v127
	v_mov_b32_e32 v82, v127
	v_mov_b32_e32 v81, v127
	v_mov_b32_e32 v80, v127
	v_mov_b32_e32 v71, v127
	v_mov_b32_e32 v70, v127
	v_mov_b32_e32 v69, v127
	v_mov_b32_e32 v68, v127
	v_mov_b32_e32 v67, v127
	v_mov_b32_e32 v66, v127
	v_mov_b32_e32 v65, v127
	v_mov_b32_e32 v64, v127
	v_mov_b32_e32 v63, v127
	v_mov_b32_e32 v62, v127
	v_mov_b32_e32 v61, v127
	v_mov_b32_e32 v60, v127
	v_mov_b32_e32 v59, v127
	v_mov_b32_e32 v58, v127
	v_mov_b32_e32 v57, v127
	v_mov_b32_e32 v56, v127
	v_mov_b32_e32 v47, v127
	v_mov_b32_e32 v46, v127
	v_mov_b32_e32 v45, v127
	v_mov_b32_e32 v44, v127
	v_mov_b32_e32 v43, v127
	v_mov_b32_e32 v42, v127
	v_mov_b32_e32 v41, v127
	v_mov_b32_e32 v40, v127
	v_mov_b32_e32 v31, v127
	v_mov_b32_e32 v30, v127
	v_mov_b32_e32 v29, v127
	v_mov_b32_e32 v28, v127
	v_mov_b32_e32 v27, v127
	v_mov_b32_e32 v26, v127
	v_mov_b32_e32 v25, v127
	v_mov_b32_e32 v24, v127
	v_mov_b32_e32 v15, v127
	v_mov_b32_e32 v14, v127
	v_mov_b32_e32 v13, v127
	v_mov_b32_e32 v12, v127
	v_mov_b32_e32 v11, v127
	v_mov_b32_e32 v10, v127
	v_mov_b32_e32 v9, v127
	v_mov_b32_e32 v8, v127
	v_mov_b32_e32 v55, v127
	v_mov_b32_e32 v54, v127
	v_mov_b32_e32 v53, v127
	v_mov_b32_e32 v52, v127
	v_mov_b32_e32 v51, v127
	v_mov_b32_e32 v50, v127
	v_mov_b32_e32 v49, v127
	v_mov_b32_e32 v48, v127
	v_mov_b32_e32 v39, v127
	v_mov_b32_e32 v38, v127
	v_mov_b32_e32 v37, v127
	v_mov_b32_e32 v36, v127
	v_mov_b32_e32 v35, v127
	v_mov_b32_e32 v34, v127
	v_mov_b32_e32 v33, v127
	v_mov_b32_e32 v32, v127
	v_mov_b32_e32 v23, v127
	v_mov_b32_e32 v22, v127
	v_mov_b32_e32 v21, v127
	v_mov_b32_e32 v20, v127
	v_mov_b32_e32 v19, v127
	v_mov_b32_e32 v18, v127
	v_mov_b32_e32 v17, v127
	v_mov_b32_e32 v16, v127
	v_mov_b32_e32 v7, v127
	v_mov_b32_e32 v6, v127
	s_waitcnt lgkmcnt(0)
	v_mov_b32_e32 v5, v127
	v_mov_b32_e32 v4, v127
	v_mov_b32_e32 v3, v127
	v_mov_b32_e32 v2, v127
	v_mov_b32_e32 v1, v127
	v_mov_b32_e32 v0, v127
	s_cbranch_vccnz .LBB0_1597
	s_add_u32 s52, s82, 0x80
	s_addc_u32 s53, s83, 0
	s_add_u32 s51, s80, 0x100
	s_addc_u32 s79, s81, 0
	s_mov_b32 s54, 0

.LBB0_1637:
	s_or_b64 exec, exec, s[12:13]
	v_cvt_f32_u32_e32 v4, v2
	s_waitcnt vmcnt(0)
	v_readfirstlane_b32 s3, v3
	v_sub_u32_e32 v3, 0, v2
	v_rcp_iflag_f32_e32 v4, v4
	v_add_u32_e32 v5, s3, v1
	v_mul_f32_e32 v4, 0x4f7ffffe, v4
	v_cvt_u32_f32_e32 v4, v4
	v_mul_lo_u32 v1, v3, v4
	v_mul_hi_u32 v1, v4, v1
	v_add_u32_e32 v1, v4, v1
	v_mul_hi_u32 v1, v5, v1
	v_mul_lo_u32 v3, v1, v2
	v_sub_u32_e32 v3, v5, v3
	v_add_u32_e32 v4, 1, v1
	v_cmp_ge_u32_e32 vcc, v3, v2
	s_nop 1
	v_cndmask_b32_e32 v1, v1, v4, vcc
	v_sub_u32_e32 v4, v3, v2
	v_cndmask_b32_e32 v3, v3, v4, vcc
	v_add_u32_e32 v4, 1, v1
	v_cmp_ge_u32_e32 vcc, v3, v2
	v_add_u32_e32 v3, 1, v5
	s_nop 0
	v_cndmask_b32_e32 v1, v1, v4, vcc
	v_mul_lo_u32 v4, v2, v1
	v_add_u32_e32 v2, v4, v2
	v_cmp_ne_u32_e32 vcc, v3, v2
	s_and_saveexec_b64 s[6:7], vcc
	s_xor_b64 s[6:7], exec, s[6:7]
	s_cbranch_execz .LBB0_1651
	s_waitcnt lgkmcnt(0)
	v_mov_b32_e32 v0, 0x2000
	buffer_inv sc1
	global_load_dword v0, v0, s[4:5] offset:1024 sc1
	s_add_u32 s14, s4, 0x2400
	s_addc_u32 s15, s5, 0
	s_waitcnt vmcnt(0)
	v_cmp_eq_u32_e32 vcc, v0, v1
	s_and_saveexec_b64 s[12:13], vcc
	s_cbranch_execz .LBB0_1650
	s_mov_b32 s3, 1
	s_mov_b64 s[16:17], 0
	v_mov_b32_e32 v0, 0
	s_branch .LBB0_1641

.LBB0_1650:
	s_or_b64 exec, exec, s[12:13]
	s_waitcnt vmcnt(0)
	s_waitcnt vmcnt(0)

.LBB0_1654:
	s_or_b64 exec, exec, s[12:13]
	buffer_inv sc1
	v_cvt_f32_u32_e32 v3, v0
	s_waitcnt vmcnt(1)
	v_readfirstlane_b32 s3, v2
	s_add_u32 s12, s38, 0x3500
	s_addc_u32 s13, s39, 0
	v_rcp_iflag_f32_e32 v3, v3
	v_add_u32_e32 v1, s3, v1
	v_add_u32_e32 v4, 1, v1
	s_mov_b64 s[14:15], -1
	v_mul_f32_e32 v2, 0x4f7ffffe, v3
	v_cvt_u32_f32_e32 v2, v2
	v_sub_u32_e32 v3, 0, v0
	v_mul_lo_u32 v3, v3, v2
	v_mul_hi_u32 v3, v2, v3
	v_add_u32_e32 v2, v2, v3
	v_mul_hi_u32 v2, v1, v2
	v_mul_lo_u32 v3, v2, v0
	v_sub_u32_e32 v1, v1, v3
	v_add_u32_e32 v5, 1, v2
	v_cmp_ge_u32_e32 vcc, v1, v0
	v_sub_u32_e32 v3, v1, v0
	s_nop 0
	v_cndmask_b32_e32 v2, v2, v5, vcc
	v_cndmask_b32_e32 v1, v1, v3, vcc
	v_add_u32_e32 v3, 1, v2
	v_cmp_ge_u32_e32 vcc, v1, v0
	s_nop 1
	v_cndmask_b32_e32 v2, v2, v3, vcc
	v_mul_lo_u32 v1, v0, v2
	v_add_u32_e32 v0, v1, v0
	v_cmp_ne_u32_e32 vcc, v4, v0
	v_mov_b64_e32 v[0:1], s[12:13]
	s_and_saveexec_b64 s[6:7], vcc
	s_cbranch_execz .LBB0_1666
	v_mov_b32_e32 v0, 0
	global_load_dword v1, v0, s[12:13] sc1
	s_mov_b64 s[18:19], 0
	s_waitcnt vmcnt(0)
	v_cmp_eq_u32_e32 vcc, v1, v2
	s_and_saveexec_b64 s[16:17], vcc
	s_cbranch_execz .LBB0_1665
	s_add_u32 s14, s38, 0x200
	s_addc_u32 s15, s39, 0
	s_mov_b32 s3, 1
	s_branch .LBB0_1658

.LBB0_1668:
	s_or_b64 exec, exec, s[6:7]
	s_mov_b64 s[6:7], exec
	v_mbcnt_lo_u32_b32 v0, s6, 0
	v_mbcnt_hi_u32_b32 v0, s7, v0
	v_cmp_eq_u32_e32 vcc, 0, v0
	s_waitcnt vmcnt(0)
	s_and_saveexec_b64 s[12:13], vcc
	s_cbranch_execz .LBB0_1670
	s_bcnt1_i32_b64 s3, s[6:7]
	v_mov_b32_e32 v0, 0x2000
	v_mov_b32_e32 v1, s3
	global_atomic_add v0, v1, s[4:5] offset:1024

.LBB0_1747:
	v_mov_b32_e32 v127, 0
	s_and_b64 vcc, exec, s[4:5]
	v_mov_b32_e32 v126, v127
	v_mov_b32_e32 v125, v127
	v_mov_b32_e32 v124, v127
	v_mov_b32_e32 v119, v127
	v_mov_b32_e32 v118, v127
	v_mov_b32_e32 v117, v127
	v_mov_b32_e32 v116, v127
	v_mov_b32_e32 v111, v127
	v_mov_b32_e32 v110, v127
	v_mov_b32_e32 v109, v127
	v_mov_b32_e32 v108, v127
	v_mov_b32_e32 v103, v127
	v_mov_b32_e32 v102, v127
	v_mov_b32_e32 v101, v127
	v_mov_b32_e32 v100, v127
	v_mov_b32_e32 v95, v127
	v_mov_b32_e32 v94, v127
	v_mov_b32_e32 v93, v127
	v_mov_b32_e32 v92, v127
	v_mov_b32_e32 v87, v127
	v_mov_b32_e32 v86, v127
	v_mov_b32_e32 v85, v127
	v_mov_b32_e32 v84, v127
	v_mov_b32_e32 v79, v127
	v_mov_b32_e32 v78, v127
	v_mov_b32_e32 v77, v127
	v_mov_b32_e32 v76, v127
	v_mov_b32_e32 v71, v127
	v_mov_b32_e32 v70, v127
	v_mov_b32_e32 v69, v127
	v_mov_b32_e32 v68, v127
	v_mov_b32_e32 v123, v127
	v_mov_b32_e32 v122, v127
	v_mov_b32_e32 v121, v127
	v_mov_b32_e32 v120, v127
	v_mov_b32_e32 v115, v127
	v_mov_b32_e32 v114, v127
	v_mov_b32_e32 v113, v127
	v_mov_b32_e32 v112, v127
	v_mov_b32_e32 v107, v127
	v_mov_b32_e32 v106, v127
	v_mov_b32_e32 v105, v127
	v_mov_b32_e32 v104, v127
	v_mov_b32_e32 v99, v127
	v_mov_b32_e32 v98, v127
	v_mov_b32_e32 v97, v127
	v_mov_b32_e32 v96, v127
	v_mov_b32_e32 v91, v127
	v_mov_b32_e32 v90, v127
	v_mov_b32_e32 v89, v127
	v_mov_b32_e32 v88, v127
	v_mov_b32_e32 v83, v127
	v_mov_b32_e32 v82, v127
	v_mov_b32_e32 v81, v127
	v_mov_b32_e32 v80, v127
	v_mov_b32_e32 v75, v127
	v_mov_b32_e32 v74, v127
	v_mov_b32_e32 v73, v127
	v_mov_b32_e32 v72, v127
	v_mov_b32_e32 v67, v127
	v_mov_b32_e32 v66, v127
	v_mov_b32_e32 v65, v127
	v_mov_b32_e32 v64, v127
	v_mov_b32_e32 v63, v127
	v_mov_b32_e32 v62, v127
	v_mov_b32_e32 v61, v127
	v_mov_b32_e32 v60, v127
	v_mov_b32_e32 v55, v127
	v_mov_b32_e32 v54, v127
	v_mov_b32_e32 v53, v127
	v_mov_b32_e32 v52, v127
	v_mov_b32_e32 v47, v127
	v_mov_b32_e32 v46, v127
	v_mov_b32_e32 v45, v127
	v_mov_b32_e32 v44, v127
	v_mov_b32_e32 v39, v127
	v_mov_b32_e32 v38, v127
	v_mov_b32_e32 v37, v127
	v_mov_b32_e32 v36, v127
	v_mov_b32_e32 v31, v127
	v_mov_b32_e32 v30, v127
	v_mov_b32_e32 v29, v127
	v_mov_b32_e32 v28, v127
	v_mov_b32_e32 v23, v127
	v_mov_b32_e32 v22, v127
	v_mov_b32_e32 v21, v127
	v_mov_b32_e32 v20, v127
	v_mov_b32_e32 v15, v127
	v_mov_b32_e32 v14, v127
	v_mov_b32_e32 v13, v127
	v_mov_b32_e32 v12, v127
	v_mov_b32_e32 v7, v127
	v_mov_b32_e32 v6, v127
	v_mov_b32_e32 v5, v127
	v_mov_b32_e32 v4, v127
	v_mov_b32_e32 v59, v127
	v_mov_b32_e32 v58, v127
	v_mov_b32_e32 v57, v127
	v_mov_b32_e32 v56, v127
	v_mov_b32_e32 v51, v127
	v_mov_b32_e32 v50, v127
	v_mov_b32_e32 v49, v127
	v_mov_b32_e32 v48, v127
	v_mov_b32_e32 v43, v127
	v_mov_b32_e32 v42, v127
	v_mov_b32_e32 v41, v127
	v_mov_b32_e32 v40, v127
	v_mov_b32_e32 v35, v127
	v_mov_b32_e32 v34, v127
	v_mov_b32_e32 v33, v127
	v_mov_b32_e32 v32, v127
	v_mov_b32_e32 v27, v127
	v_mov_b32_e32 v26, v127
	v_mov_b32_e32 v25, v127
	v_mov_b32_e32 v24, v127
	v_mov_b32_e32 v19, v127
	v_mov_b32_e32 v18, v127
	v_mov_b32_e32 v17, v127
	v_mov_b32_e32 v16, v127
	v_mov_b32_e32 v11, v127
	v_mov_b32_e32 v10, v127
	v_mov_b32_e32 v9, v127
	v_mov_b32_e32 v8, v127
	v_mov_b32_e32 v3, v127
	v_mov_b32_e32 v2, v127
	v_mov_b32_e32 v1, v127
	v_mov_b32_e32 v0, v127
	s_cbranch_vccnz .LBB0_1750
	s_add_u32 s46, s46, 0x80
	s_addc_u32 s47, s47, 0
	s_add_u32 s43, s48, 0x100
	s_addc_u32 s79, s49, 0
	s_mov_b32 s48, 0

.LBB0_1830:
	v_mov_b32_e32 v127, 0
	s_and_b64 vcc, exec, s[6:7]
	v_mov_b32_e32 v126, v127
	v_mov_b32_e32 v125, v127
	v_mov_b32_e32 v124, v127
	v_mov_b32_e32 v123, v127
	v_mov_b32_e32 v122, v127
	v_mov_b32_e32 v121, v127
	v_mov_b32_e32 v120, v127
	v_mov_b32_e32 v111, v127
	v_mov_b32_e32 v110, v127
	v_mov_b32_e32 v109, v127
	v_mov_b32_e32 v108, v127
	v_mov_b32_e32 v107, v127
	v_mov_b32_e32 v106, v127
	v_mov_b32_e32 v105, v127
	v_mov_b32_e32 v104, v127
	v_mov_b32_e32 v95, v127
	v_mov_b32_e32 v94, v127
	v_mov_b32_e32 v93, v127
	v_mov_b32_e32 v92, v127
	v_mov_b32_e32 v91, v127
	v_mov_b32_e32 v90, v127
	v_mov_b32_e32 v89, v127
	v_mov_b32_e32 v88, v127
	v_mov_b32_e32 v79, v127
	v_mov_b32_e32 v78, v127
	v_mov_b32_e32 v77, v127
	v_mov_b32_e32 v76, v127
	v_mov_b32_e32 v75, v127
	v_mov_b32_e32 v74, v127
	v_mov_b32_e32 v73, v127
	v_mov_b32_e32 v72, v127
	v_mov_b32_e32 v119, v127
	v_mov_b32_e32 v118, v127
	v_mov_b32_e32 v117, v127
	v_mov_b32_e32 v116, v127
	v_mov_b32_e32 v115, v127
	v_mov_b32_e32 v114, v127
	v_mov_b32_e32 v113, v127
	v_mov_b32_e32 v112, v127
	v_mov_b32_e32 v103, v127
	v_mov_b32_e32 v102, v127
	v_mov_b32_e32 v101, v127
	v_mov_b32_e32 v100, v127
	v_mov_b32_e32 v99, v127
	v_mov_b32_e32 v98, v127
	v_mov_b32_e32 v97, v127
	v_mov_b32_e32 v96, v127
	v_mov_b32_e32 v87, v127
	v_mov_b32_e32 v86, v127
	v_mov_b32_e32 v85, v127
	v_mov_b32_e32 v84, v127
	v_mov_b32_e32 v83, v127
	v_mov_b32_e32 v82, v127
	v_mov_b32_e32 v81, v127
	v_mov_b32_e32 v80, v127
	v_mov_b32_e32 v71, v127
	v_mov_b32_e32 v70, v127
	v_mov_b32_e32 v69, v127
	v_mov_b32_e32 v68, v127
	v_mov_b32_e32 v67, v127
	v_mov_b32_e32 v66, v127
	v_mov_b32_e32 v65, v127
	v_mov_b32_e32 v64, v127
	v_mov_b32_e32 v63, v127
	v_mov_b32_e32 v62, v127
	v_mov_b32_e32 v61, v127
	v_mov_b32_e32 v60, v127
	v_mov_b32_e32 v59, v127
	v_mov_b32_e32 v58, v127
	v_mov_b32_e32 v57, v127
	v_mov_b32_e32 v56, v127
	v_mov_b32_e32 v47, v127
	v_mov_b32_e32 v46, v127
	v_mov_b32_e32 v45, v127
	v_mov_b32_e32 v44, v127
	v_mov_b32_e32 v43, v127
	v_mov_b32_e32 v42, v127
	v_mov_b32_e32 v41, v127
	v_mov_b32_e32 v40, v127
	v_mov_b32_e32 v31, v127
	v_mov_b32_e32 v30, v127
	v_mov_b32_e32 v29, v127
	v_mov_b32_e32 v28, v127
	v_mov_b32_e32 v27, v127
	v_mov_b32_e32 v26, v127
	v_mov_b32_e32 v25, v127
	v_mov_b32_e32 v24, v127
	v_mov_b32_e32 v15, v127
	v_mov_b32_e32 v14, v127
	v_mov_b32_e32 v13, v127
	v_mov_b32_e32 v12, v127
	v_mov_b32_e32 v11, v127
	v_mov_b32_e32 v10, v127
	v_mov_b32_e32 v9, v127
	v_mov_b32_e32 v8, v127
	v_mov_b32_e32 v55, v127
	v_mov_b32_e32 v54, v127
	v_mov_b32_e32 v53, v127
	v_mov_b32_e32 v52, v127
	v_mov_b32_e32 v51, v127
	v_mov_b32_e32 v50, v127
	v_mov_b32_e32 v49, v127
	v_mov_b32_e32 v48, v127
	v_mov_b32_e32 v39, v127
	v_mov_b32_e32 v38, v127
	v_mov_b32_e32 v37, v127
	v_mov_b32_e32 v36, v127
	v_mov_b32_e32 v35, v127
	v_mov_b32_e32 v34, v127
	v_mov_b32_e32 v33, v127
	v_mov_b32_e32 v32, v127
	v_mov_b32_e32 v23, v127
	v_mov_b32_e32 v22, v127
	v_mov_b32_e32 v21, v127
	v_mov_b32_e32 v20, v127
	v_mov_b32_e32 v19, v127
	v_mov_b32_e32 v18, v127
	v_mov_b32_e32 v17, v127
	v_mov_b32_e32 v16, v127
	v_mov_b32_e32 v7, v127
	v_mov_b32_e32 v6, v127
	s_waitcnt lgkmcnt(0)
	v_mov_b32_e32 v5, v127
	v_mov_b32_e32 v4, v127
	v_mov_b32_e32 v3, v127
	v_mov_b32_e32 v2, v127
	v_mov_b32_e32 v1, v127
	v_mov_b32_e32 v0, v127
	s_cbranch_vccnz .LBB0_1834
	s_add_u32 s52, s80, 0x80
	s_addc_u32 s53, s81, 0
	s_add_u32 s51, s78, 0x100
	s_addc_u32 s77, s79, 0
	s_mov_b32 s54, 0

.LBB0_1874:
	s_or_b64 exec, exec, s[6:7]
	v_cvt_f32_u32_e32 v4, v2
	s_waitcnt vmcnt(0)
	v_readfirstlane_b32 s4, v3
	v_sub_u32_e32 v3, 0, v2
	v_rcp_iflag_f32_e32 v4, v4
	v_add_u32_e32 v5, s4, v1
	v_mul_f32_e32 v4, 0x4f7ffffe, v4
	v_cvt_u32_f32_e32 v4, v4
	v_mul_lo_u32 v1, v3, v4
	v_mul_hi_u32 v1, v4, v1
	v_add_u32_e32 v1, v4, v1
	v_mul_hi_u32 v1, v5, v1
	v_mul_lo_u32 v3, v1, v2
	v_sub_u32_e32 v3, v5, v3
	v_add_u32_e32 v4, 1, v1
	v_cmp_ge_u32_e32 vcc, v3, v2
	s_nop 1
	v_cndmask_b32_e32 v1, v1, v4, vcc
	v_sub_u32_e32 v4, v3, v2
	v_cndmask_b32_e32 v3, v3, v4, vcc
	v_add_u32_e32 v4, 1, v1
	v_cmp_ge_u32_e32 vcc, v3, v2
	v_add_u32_e32 v3, 1, v5
	s_nop 0
	v_cndmask_b32_e32 v1, v1, v4, vcc
	v_mul_lo_u32 v4, v2, v1
	v_add_u32_e32 v2, v4, v2
	v_cmp_ne_u32_e32 vcc, v3, v2
	s_and_saveexec_b64 s[4:5], vcc
	s_xor_b64 s[4:5], exec, s[4:5]
	s_cbranch_execz .LBB0_1888
	s_waitcnt lgkmcnt(0)
	v_mov_b32_e32 v0, 0x2000
	buffer_inv sc1
	global_load_dword v0, v0, s[2:3] offset:1024 sc1
	s_add_u32 s10, s2, 0x2400
	s_addc_u32 s11, s3, 0
	s_waitcnt vmcnt(0)
	v_cmp_eq_u32_e32 vcc, v0, v1
	s_and_saveexec_b64 s[6:7], vcc
	s_cbranch_execz .LBB0_1887
	s_mov_b32 s24, 1
	s_mov_b64 s[12:13], 0
	v_mov_b32_e32 v0, 0
	s_branch .LBB0_1878

.LBB0_1887:
	s_or_b64 exec, exec, s[6:7]
	s_waitcnt vmcnt(0)
	s_waitcnt vmcnt(0)

.LBB0_1891:
	s_or_b64 exec, exec, s[6:7]
	buffer_inv sc1
	v_cvt_f32_u32_e32 v3, v0
	s_waitcnt vmcnt(1)
	v_readfirstlane_b32 s4, v2
	s_add_u32 s6, s38, 0x3500
	s_addc_u32 s7, s39, 0
	v_rcp_iflag_f32_e32 v3, v3
	v_add_u32_e32 v1, s4, v1
	v_add_u32_e32 v4, 1, v1
	s_mov_b64 s[10:11], -1
	v_mul_f32_e32 v2, 0x4f7ffffe, v3
	v_cvt_u32_f32_e32 v2, v2
	v_sub_u32_e32 v3, 0, v0
	v_mul_lo_u32 v3, v3, v2
	v_mul_hi_u32 v3, v2, v3
	v_add_u32_e32 v2, v2, v3
	v_mul_hi_u32 v2, v1, v2
	v_mul_lo_u32 v3, v2, v0
	v_sub_u32_e32 v1, v1, v3
	v_add_u32_e32 v5, 1, v2
	v_cmp_ge_u32_e32 vcc, v1, v0
	v_sub_u32_e32 v3, v1, v0
	s_nop 0
	v_cndmask_b32_e32 v2, v2, v5, vcc
	v_cndmask_b32_e32 v1, v1, v3, vcc
	v_add_u32_e32 v3, 1, v2
	v_cmp_ge_u32_e32 vcc, v1, v0
	s_nop 1
	v_cndmask_b32_e32 v2, v2, v3, vcc
	v_mul_lo_u32 v1, v0, v2
	v_add_u32_e32 v0, v1, v0
	v_cmp_ne_u32_e32 vcc, v4, v0
	v_mov_b64_e32 v[0:1], s[6:7]
	s_and_saveexec_b64 s[4:5], vcc
	s_cbranch_execz .LBB0_1903
	v_mov_b32_e32 v0, 0
	global_load_dword v1, v0, s[6:7] sc1
	s_mov_b64 s[14:15], 0
	s_waitcnt vmcnt(0)
	v_cmp_eq_u32_e32 vcc, v1, v2
	s_and_saveexec_b64 s[12:13], vcc
	s_cbranch_execz .LBB0_1902
	s_add_u32 s10, s38, 0x200
	s_addc_u32 s11, s39, 0
	s_mov_b32 s26, 1
	s_branch .LBB0_1895

.LBB0_1905:
	s_or_b64 exec, exec, s[4:5]
	s_mov_b64 s[4:5], exec
	v_mbcnt_lo_u32_b32 v0, s4, 0
	v_mbcnt_hi_u32_b32 v0, s5, v0
	v_cmp_eq_u32_e32 vcc, 0, v0
	s_waitcnt vmcnt(0)
	s_and_saveexec_b64 s[6:7], vcc
	s_cbranch_execz .LBB0_1907
	s_bcnt1_i32_b64 s4, s[4:5]
	v_mov_b32_e32 v0, 0x2000
	v_mov_b32_e32 v1, s4
	global_atomic_add v0, v1, s[2:3] offset:1024
